# C1 (cumulative hand-off chain) + k^d read four steps ahead with one wait per two steps + one iteration-counter add + y base pointer advanced on the scalar side
# speedup vs baseline: 1.0085x; 1.0021x over previous
.Lsc_G:
	v_add_u32_e32 v1, 0xffffff00, v173
	v_lshrrev_b32_e32 v2, 3, v1
	v_and_b32_e32 v3, 7, v1
	s_and_b32 s8, s4, 7
	s_bfe_u32 s10, s4, 0x20003
	s_lshr_b32 s11, s4, 7
	s_bfe_u32 s9, s4, 0x20005
	s_lshl_b32 s9, s9, 13
	v_readlane_b32 s50, v242, 0
	v_readlane_b32 s51, v242, 1
	v_readlane_b32 s16, v242, 62
	s_load_dwordx4 s[12:15], s[50:51], 0x68
	s_add_u32 s36, s90, 0x5e00000
	s_addc_u32 s37, s91, 0
	s_add_u32 s38, s90, 0x7e00000
	s_addc_u32 s39, s91, 0
	s_add_u32 s44, s90, 0x9e00000
	s_addc_u32 s45, s91, 0
	s_add_u32 s46, s90, 0x1c00000
	s_addc_u32 s47, s91, 0
	s_lshl_b32 s68, s11, 25
	s_add_u32 s69, s68, 0x13e00000
	s_add_u32 s40, s90, s69
	s_addc_u32 s41, s91, 0
	s_add_u32 s69, s68, 0x17e00000
	s_add_u32 s42, s90, s69
	s_addc_u32 s43, s91, 0
	s_lshl_b32 s68, s11, 26
	s_add_u32 s68, s68, 0xbe00000
	s_add_u32 s48, s90, s68
	s_addc_u32 s49, s91, 0
	s_cmp_eq_u32 s11, 0
	s_mov_b32 s54, 0x8000
	s_movk_i32 s55, 0x400
	s_mov_b32 s64, 0x10000
	s_cselect_b32 s54, s54, 0xffff8000
	s_cselect_b32 s55, s55, 0xfffffc00
	s_cselect_b32 s64, s64, 0xffff0000
	s_cselect_b64 vcc, -1, 0
	s_ashr_i32 s50, s64, 31
	v_sub_u32_e32 v4, 0x1fff, v2
	s_nop 3
	v_cndmask_b32_e32 v4, v4, v2, vcc
	v_add_u32_e32 v4, s9, v4
	s_lshl_b32 s68, s8, 7
	v_lshlrev_b32_e32 v5, 10, v4
	v_lshl_add_u32 v5, v3, 3, v5
	v_add_u32_e32 v5, s68, v5
	s_lshl_b32 s69, s8, 2
	v_lshlrev_b32_e32 v6, 5, v4
	v_add_u32_e32 v6, s69, v6
	s_lshl_b32 s69, s10, 5
	s_add_i32 s69, s69, s68
	v_lshlrev_b32_e32 v9, 10, v4
	v_lshl_add_u32 v9, v3, 2, v9
	v_add_u32_e32 v9, s69, v9
	s_lshl_b32 s65, s69, 1
	v_mul_u32_u24_e32 v8, 1024, v2
	v_lshl_add_u32 v8, v3, 4, v8
	v_add_u32_e32 v138, 512, v8
	v_add_u32_e32 v140, 35328, v8
	v_add_u32_e32 v152, -4, v0
	v_mul_u32_u24_e32 v152, 4608, v152
	v_add_u32_e32 v152, 143936, v152
	v_and_b32_e32 v156, 7, v2
	v_lshlrev_b32_e32 v153, 8, v156
	v_lshl_add_u32 v153, v3, 4, v153
	v_add_u32_e32 v153, v152, v153
	v_and_b32_e32 v154, 63, v1
	v_lshl_add_u32 v154, v154, 2, v152
	v_add_u32_e32 v155, 2048, v154
	v_add_u32_e32 v139, -1, v2
	v_mul_u32_u24_e32 v139, 1024, v139
	v_lshl_add_u32 v139, v3, 4, v139
	v_add_u32_e32 v141, 35328, v139
	v_add_u32_e32 v139, 512, v139
	v_cmp_eq_u32_e32 vcc, 0, v2
	s_nop 1
	v_cndmask_b32_e32 v139, v139, v152, vcc
	v_cndmask_b32_e32 v141, v141, v152, vcc
	v_lshrrev_b32_e32 v158, 3, v2
	v_lshlrev_b32_e32 v158, 8, v158
	v_lshl_add_u32 v158, v3, 4, v158
	v_and_b32_e32 v159, 63, v1
	v_lshlrev_b32_e32 v159, 2, v159
	v_add_u32_e32 v106, -4, v0
	v_lshl_add_u32 v159, v106, 8, v159
	v_add_u32_e32 v159, 33792, v159
	v_add_u32_e32 v106, -4, v0
	v_lshlrev_b32_e32 v162, 2, v106
	v_add_u32_e32 v162, 139808, v162
	v_mov_b32_e32 v163, 139808
	v_and_b32_e32 v181, 63, v1
	v_lshlrev_b32_e32 v181, 2, v181
	v_add_u32_e32 v181, 139840, v181
	v_lshl_add_u32 v180, v106, 8, v181
	v_cmp_gt_u32_e32 vcc, v106, v169
	s_nop 1
	v_cndmask_b32_e64 v174, 0, -1, vcc
	v_mov_b32_e32 v177, 0x7fffffff
	v_cndmask_b32_e32 v177, v177, v169, vcc
	v_cmp_lt_u32_e32 vcc, 1, v106
	s_nop 1
	v_cndmask_b32_e64 v175, 0, -1, vcc
	v_mov_b32_e32 v178, 0x7fffffff
	v_cndmask_b32_e32 v178, v178, v169, vcc
	v_cmp_lt_u32_e32 vcc, 2, v106
	s_nop 1
	v_cndmask_b32_e64 v176, 0, -1, vcc
	v_mov_b32_e32 v179, 0x7fffffff
	v_cndmask_b32_e32 v179, v179, v169, vcc
	v_cmp_lt_u32_e32 vcc, 0, v106
	v_add_u32_e32 v175, 0xffffff00, v180
	v_add_u32_e32 v163, -4, v162
	s_nop 1
	v_cndmask_b32_e32 v175, v181, v175, vcc
	v_cndmask_b32_e32 v163, v162, v163, vcc
	v_add_u32_e32 v158, 32768, v158
	v_mul_u32_u24_e32 v142, 288, v3
	v_lshl_add_u32 v142, v2, 2, v142
	v_add_u32_e32 v143, 71936, v142
	v_add_u32_e32 v142, 69632, v142
	s_lshl_b32 s69, s8, 6
	s_add_i32 s69, s69, s16
	v_lshl_add_u32 v106, v3, 2, s69
	v_lshlrev_b32_e32 v106, 2, v106
	s_waitcnt lgkmcnt(0)
	global_load_dwordx4 v[12:15], v106, s[12:13]
	global_load_dwordx4 v[16:19], v106, s[12:13] offset:128
	global_load_dwordx4 v[20:23], v106, s[14:15]
	global_load_dwordx4 v[24:27], v106, s[14:15] offset:128
	global_load_dwordx2 v[28:29], v5, s[36:37]
	global_load_dwordx2 v[30:31], v5, s[36:37] offset:64
	global_load_dwordx2 v[32:33], v5, s[38:39]
	global_load_dwordx2 v[34:35], v5, s[38:39] offset:64
	global_load_dwordx2 v[36:37], v5, s[40:41]
	global_load_dwordx2 v[38:39], v5, s[40:41] offset:64
	global_load_dwordx2 v[40:41], v5, s[42:43]
	global_load_dwordx2 v[42:43], v5, s[42:43] offset:64
	global_load_dword v44, v6, s[46:47]
	global_load_dword v45, v9, s[44:45]
	v_add_u32_e32 v5, s54, v5
	v_add_u32_e32 v6, s55, v6
	v_add_u32_e32 v9, s54, v9
	global_load_dwordx2 v[46:47], v5, s[36:37]
	global_load_dwordx2 v[48:49], v5, s[36:37] offset:64
	global_load_dwordx2 v[50:51], v5, s[38:39]
	global_load_dwordx2 v[52:53], v5, s[38:39] offset:64
	global_load_dwordx2 v[54:55], v5, s[40:41]
	global_load_dwordx2 v[56:57], v5, s[40:41] offset:64
	global_load_dwordx2 v[58:59], v5, s[42:43]
	global_load_dwordx2 v[60:61], v5, s[42:43] offset:64
	global_load_dword v62, v6, s[46:47]
	global_load_dword v63, v9, s[44:45]
	v_add_u32_e32 v5, s54, v5
	v_add_u32_e32 v6, s55, v6
	v_add_u32_e32 v9, s54, v9
	v_and_b32_e32 v166, 15, v1
	v_lshrrev_b32_e32 v167, 4, v1
	v_sub_u32_e32 v4, 0x1fff, v167
	s_cmp_eq_u32 s11, 0
	s_cselect_b64 vcc, -1, 0
	s_nop 3
	v_cndmask_b32_e32 v4, v4, v167, vcc
	v_add_u32_e32 v4, s9, v4
	v_lshlrev_b32_e32 v7, 11, v4
	v_lshl_add_u32 v7, v166, 2, v7
	v_add_u32_e32 v7, s65, v7
	s_ashr_i32 s65, s64, 1
	v_add_u32_e32 v165, s65, v7
	v_lshlrev_b32_e32 v11, 10, v167
	v_lshl_add_u32 v11, v166, 6, v11
	v_add_u32_e32 v11, 74240, v11
	v_lshrrev_b32_e32 v166, 2, v166
	v_add_u32_e32 v2, 0, v166
	v_and_b32_e32 v2, 3, v2
	v_lshl_add_u32 v2, v2, 4, v11
	v_add_u32_e32 v3, 1, v166
	v_and_b32_e32 v3, 3, v3
	v_lshl_add_u32 v3, v3, 4, v11
	v_add_u32_e32 v4, 2, v166
	v_and_b32_e32 v4, 3, v4
	v_lshl_add_u32 v4, v4, 4, v11
	v_add_u32_e32 v10, 3, v166
	v_and_b32_e32 v10, 3, v10
	v_lshl_add_u32 v10, v10, 4, v11
	s_waitcnt vmcnt(20)
	v_pk_add_f32 v[190:191], v[20:21], 1.0 op_sel_hi:[1,0] neg_lo:[1,0] neg_hi:[1,0]
	v_pk_add_f32 v[192:193], v[22:23], 1.0 op_sel_hi:[1,0] neg_lo:[1,0] neg_hi:[1,0]
	v_pk_add_f32 v[194:195], v[24:25], 1.0 op_sel_hi:[1,0] neg_lo:[1,0] neg_hi:[1,0]
	v_pk_add_f32 v[196:197], v[26:27], 1.0 op_sel_hi:[1,0] neg_lo:[1,0] neg_hi:[1,0]
	v_cmp_eq_u32_e64 s[12:13], 0, v156
	s_mov_b32 s14, 0x3fb8aa3b
	s_mov_b32 s6, 0
	v_mov_b32_e32 v144, 139792
	v_mov_b32_e32 v145, v164
	v_mov_b32_e32 v146, 0
	s_waitcnt vmcnt(10)
	v_lshlrev_b32_e32 v64, 16, v36
	v_and_b32_e32 v65, 0xffff0000, v36
	v_lshlrev_b32_e32 v66, 16, v37
	v_and_b32_e32 v67, 0xffff0000, v37
	v_lshlrev_b32_e32 v68, 16, v38
	v_and_b32_e32 v69, 0xffff0000, v38
	v_lshlrev_b32_e32 v70, 16, v39
	v_and_b32_e32 v71, 0xffff0000, v39
	ds_write_b128 v153, v[64:67]
	ds_write_b128 v153, v[68:71] offset:128
	s_waitcnt lgkmcnt(0)
	ds_read_b32 v124, v154 offset:0
	ds_read_b32 v125, v154 offset:256
	ds_read_b32 v126, v154 offset:512
	ds_read_b32 v127, v154 offset:768
	ds_read_b32 v128, v154 offset:1024
	ds_read_b32 v129, v154 offset:1280
	ds_read_b32 v130, v154 offset:1536
	ds_read_b32 v131, v154 offset:1792
	v_lshlrev_b32_e32 v108, 16, v32
	v_and_b32_e32 v109, 0xffff0000, v32
	v_lshlrev_b32_e32 v110, 16, v40
	v_and_b32_e32 v111, 0xffff0000, v40
	v_lshlrev_b32_e32 v96, 16, v28
	v_and_b32_e32 v97, 0xffff0000, v28
	v_pk_mul_f32 v[114:115], v[12:13], v[108:109]
	v_pk_fma_f32 v[112:113], v[20:21], v[110:111], v[190:191]
	v_pk_mul_f32 v[88:89], v[44:45], v[114:115] op_sel_hi:[0,1]
	v_pk_mul_f32 v[72:73], v[112:113], v[108:109]
	v_pk_mul_f32 v[80:81], v[88:89], v[110:111]
	v_lshlrev_b32_e32 v108, 16, v33
	v_and_b32_e32 v109, 0xffff0000, v33
	v_lshlrev_b32_e32 v110, 16, v41
	v_and_b32_e32 v111, 0xffff0000, v41
	v_lshlrev_b32_e32 v98, 16, v29
	v_and_b32_e32 v99, 0xffff0000, v29
	v_pk_mul_f32 v[114:115], v[14:15], v[108:109]
	v_pk_fma_f32 v[112:113], v[22:23], v[110:111], v[192:193]
	v_pk_mul_f32 v[90:91], v[44:45], v[114:115] op_sel_hi:[0,1]
	v_pk_mul_f32 v[74:75], v[112:113], v[108:109]
	v_pk_mul_f32 v[82:83], v[90:91], v[110:111]
	v_lshlrev_b32_e32 v108, 16, v34
	v_and_b32_e32 v109, 0xffff0000, v34
	v_lshlrev_b32_e32 v110, 16, v42
	v_and_b32_e32 v111, 0xffff0000, v42
	v_lshlrev_b32_e32 v100, 16, v30
	v_and_b32_e32 v101, 0xffff0000, v30
	v_pk_mul_f32 v[114:115], v[16:17], v[108:109]
	v_pk_fma_f32 v[112:113], v[24:25], v[110:111], v[194:195]
	v_pk_mul_f32 v[92:93], v[44:45], v[114:115] op_sel_hi:[0,1]
	v_pk_mul_f32 v[76:77], v[112:113], v[108:109]
	v_pk_mul_f32 v[84:85], v[92:93], v[110:111]
	v_lshlrev_b32_e32 v108, 16, v35
	v_and_b32_e32 v109, 0xffff0000, v35
	v_lshlrev_b32_e32 v110, 16, v43
	v_and_b32_e32 v111, 0xffff0000, v43
	v_lshlrev_b32_e32 v102, 16, v31
	v_and_b32_e32 v103, 0xffff0000, v31
	v_pk_mul_f32 v[114:115], v[18:19], v[108:109]
	v_pk_fma_f32 v[112:113], v[26:27], v[110:111], v[196:197]
	v_pk_mul_f32 v[94:95], v[44:45], v[114:115] op_sel_hi:[0,1]
	v_pk_mul_f32 v[78:79], v[112:113], v[108:109]
	v_pk_mul_f32 v[86:87], v[94:95], v[110:111]
	v_lshlrev_b32_e32 v104, 16, v45
	v_and_b32_e32 v105, 0xffff0000, v45
	s_waitcnt lgkmcnt(0)
	v_add_f32_e32 v125, v124, v125
	v_add_f32_e32 v126, v125, v126
	v_add_f32_e32 v127, v126, v127
	v_add_f32_e32 v128, v127, v128
	v_add_f32_e32 v129, v128, v129
	v_add_f32_e32 v130, v129, v130
	v_add_f32_e32 v131, v130, v131
	s_and_b32 s72, s6, 3
	s_lshl_b32 s72, s72, 10
	v_add_u32_e32 v182, s72, v180
	v_add_u32_e32 v183, s72, v175
	v_add_u32_e32 v146, 1, v146
	s_add_u32 s73, s6, 1
	s_mov_b32 s69, 0x100000

.Lsc_gf_go1:
	ds_read_b32 v185, v183
	s_waitcnt lgkmcnt(0)
	v_and_b32_e32 v185, v174, v185
	v_fma_f32 v189, v131, s14, v185
	ds_write_b32 v182, v189
	s_waitcnt lgkmcnt(0)
	ds_write_b32 v162, v146
	v_fma_f32 v124, v124, s14, v185
	v_fma_f32 v125, v125, s14, v185
	v_fma_f32 v126, v126, s14, v185
	v_fma_f32 v127, v127, s14, v185
	v_fma_f32 v128, v128, s14, v185
	v_fma_f32 v129, v129, s14, v185
	v_fma_f32 v130, v130, s14, v185
	v_fma_f32 v131, v131, s14, v185
	v_exp_f32_e64 v188, -v185
	v_exp_f32_e64 v124, -v124
	v_exp_f32_e64 v125, -v125
	v_exp_f32_e64 v126, -v126
	v_exp_f32_e64 v127, -v127
	v_exp_f32_e64 v128, -v128
	v_exp_f32_e64 v129, -v129
	v_exp_f32_e64 v130, -v130
	v_exp_f32_e64 v131, -v131
	s_nop 0
	ds_write_b32 v155, v188
	ds_write_b32 v155, v124 offset:256
	ds_write_b32 v155, v125 offset:512
	ds_write_b32 v155, v126 offset:768
	ds_write_b32 v155, v127 offset:1024
	ds_write_b32 v155, v128 offset:1280
	ds_write_b32 v155, v129 offset:1536
	ds_write_b32 v155, v130 offset:1792
	ds_write_b32 v155, v131 offset:2048
	v_mov_b32_e32 v161, v131
	s_waitcnt lgkmcnt(0)
	ds_read_b128 v[64:67], v153 offset:2048
	ds_read_b128 v[68:71], v153 offset:2176
	ds_read_b128 v[116:119], v153 offset:2304
	ds_read_b128 v[120:123], v153 offset:2432
	s_waitcnt lgkmcnt(0)
	v_rcp_f32_e32 v124, v116
	v_rcp_f32_e32 v125, v117
	v_rcp_f32_e32 v126, v118
	v_rcp_f32_e32 v127, v119
	v_rcp_f32_e32 v128, v120
	v_rcp_f32_e32 v129, v121
	v_rcp_f32_e32 v130, v122
	v_rcp_f32_e32 v131, v123
	s_nop 1
	v_pk_mul_f32 v[72:73], v[72:73], v[124:125]
	v_pk_mul_f32 v[80:81], v[80:81], v[124:125]
	v_pk_mul_f32 v[88:89], v[88:89], v[64:65]
	v_pk_mul_f32 v[96:97], v[96:97], v[116:117]
	v_pk_mul_f32 v[74:75], v[74:75], v[126:127]
	v_pk_mul_f32 v[82:83], v[82:83], v[126:127]
	v_pk_mul_f32 v[90:91], v[90:91], v[66:67]
	v_pk_mul_f32 v[98:99], v[98:99], v[118:119]
	v_pk_mul_f32 v[76:77], v[76:77], v[128:129]
	v_pk_mul_f32 v[84:85], v[84:85], v[128:129]
	v_pk_mul_f32 v[92:93], v[92:93], v[68:69]
	v_pk_mul_f32 v[100:101], v[100:101], v[120:121]
	v_pk_mul_f32 v[78:79], v[78:79], v[130:131]
	v_pk_mul_f32 v[86:87], v[86:87], v[130:131]
	v_pk_mul_f32 v[94:95], v[94:95], v[70:71]
	v_pk_mul_f32 v[102:103], v[102:103], v[122:123]
	global_load_dwordx2 v[28:29], v5, s[36:37]
	global_load_dwordx2 v[30:31], v5, s[36:37] offset:64
	global_load_dwordx2 v[32:33], v5, s[38:39]
	global_load_dwordx2 v[34:35], v5, s[38:39] offset:64
	global_load_dwordx2 v[36:37], v5, s[40:41]
	global_load_dwordx2 v[38:39], v5, s[40:41] offset:64
	global_load_dwordx2 v[40:41], v5, s[42:43]
	global_load_dwordx2 v[42:43], v5, s[42:43] offset:64
	global_load_dword v44, v6, s[46:47]
	global_load_dword v45, v9, s[44:45]
	v_add_u32_e32 v5, s54, v5
	v_add_u32_e32 v6, s55, v6
	v_add_u32_e32 v9, s54, v9
	ds_write_b32 v159, v161 offset:0
	ds_write_b128 v8, v[72:75] offset:0
	s_sleep 1
	ds_write_b128 v8, v[76:79] offset:128
	ds_write_b128 v8, v[80:83] offset:256
	s_sleep 1
	ds_write_b128 v8, v[84:87] offset:384
	ds_write2_b32 v138, v96, v97 offset0:1 offset1:3
	s_sleep 1
	ds_write2_b32 v139, v88, v89 offset0:0 offset1:2
	ds_write2_b32 v138, v98, v99 offset0:65 offset1:67
	s_sleep 1
	ds_write2_b32 v139, v90, v91 offset0:64 offset1:66
	ds_write2_b32 v138, v100, v101 offset0:33 offset1:35
	s_sleep 1
	ds_write2_b32 v139, v92, v93 offset0:32 offset1:34
	ds_write2_b32 v138, v102, v103 offset0:97 offset1:99
	s_sleep 1
	ds_write2_b32 v139, v94, v95 offset0:96 offset1:98
	ds_write2_b32 v142, v104, v105 offset1:36
	s_sleep 1
	s_cmp_lg_u32 s7, 4
	s_cbranch_scc1 .Lsc_nokb1
	s_and_saveexec_b64 s[68:69], s[12:13]
	ds_write_b128 v158, v[88:91] offset:0
	ds_write_b128 v158, v[92:95] offset:128
	s_mov_b64 exec, s[68:69]
.Lsc_nokb1:
	s_add_i32 s6, s6, 1
	s_waitcnt lgkmcnt(0)
	ds_write_b32 v145, v146
	s_waitcnt vmcnt(10)
	v_lshlrev_b32_e32 v64, 16, v54
	v_and_b32_e32 v65, 0xffff0000, v54
	v_lshlrev_b32_e32 v66, 16, v55
	v_and_b32_e32 v67, 0xffff0000, v55
	v_lshlrev_b32_e32 v68, 16, v56
	v_and_b32_e32 v69, 0xffff0000, v56
	v_lshlrev_b32_e32 v70, 16, v57
	v_and_b32_e32 v71, 0xffff0000, v57
	ds_write_b128 v153, v[64:67]
	ds_write_b128 v153, v[68:71] offset:128
	s_waitcnt lgkmcnt(0)
	ds_read_b32 v124, v154 offset:0
	ds_read_b32 v125, v154 offset:256
	ds_read_b32 v126, v154 offset:512
	ds_read_b32 v127, v154 offset:768
	ds_read_b32 v128, v154 offset:1024
	ds_read_b32 v129, v154 offset:1280
	ds_read_b32 v130, v154 offset:1536
	ds_read_b32 v131, v154 offset:1792
	v_lshlrev_b32_e32 v108, 16, v50
	v_and_b32_e32 v109, 0xffff0000, v50
	v_lshlrev_b32_e32 v110, 16, v58
	v_and_b32_e32 v111, 0xffff0000, v58
	v_lshlrev_b32_e32 v96, 16, v46
	v_and_b32_e32 v97, 0xffff0000, v46
	v_pk_mul_f32 v[114:115], v[12:13], v[108:109]
	v_pk_fma_f32 v[112:113], v[20:21], v[110:111], v[190:191]
	v_pk_mul_f32 v[88:89], v[62:63], v[114:115] op_sel_hi:[0,1]
	v_pk_mul_f32 v[72:73], v[112:113], v[108:109]
	v_pk_mul_f32 v[80:81], v[88:89], v[110:111]
	v_lshlrev_b32_e32 v108, 16, v51
	v_and_b32_e32 v109, 0xffff0000, v51
	v_lshlrev_b32_e32 v110, 16, v59
	v_and_b32_e32 v111, 0xffff0000, v59
	v_lshlrev_b32_e32 v98, 16, v47
	v_and_b32_e32 v99, 0xffff0000, v47
	v_pk_mul_f32 v[114:115], v[14:15], v[108:109]
	v_pk_fma_f32 v[112:113], v[22:23], v[110:111], v[192:193]
	v_pk_mul_f32 v[90:91], v[62:63], v[114:115] op_sel_hi:[0,1]
	v_pk_mul_f32 v[74:75], v[112:113], v[108:109]
	v_pk_mul_f32 v[82:83], v[90:91], v[110:111]
	v_lshlrev_b32_e32 v108, 16, v52
	v_and_b32_e32 v109, 0xffff0000, v52
	v_lshlrev_b32_e32 v110, 16, v60
	v_and_b32_e32 v111, 0xffff0000, v60
	v_lshlrev_b32_e32 v100, 16, v48
	v_and_b32_e32 v101, 0xffff0000, v48
	v_pk_mul_f32 v[114:115], v[16:17], v[108:109]
	v_pk_fma_f32 v[112:113], v[24:25], v[110:111], v[194:195]
	v_pk_mul_f32 v[92:93], v[62:63], v[114:115] op_sel_hi:[0,1]
	v_pk_mul_f32 v[76:77], v[112:113], v[108:109]
	v_pk_mul_f32 v[84:85], v[92:93], v[110:111]
	v_lshlrev_b32_e32 v108, 16, v53
	v_and_b32_e32 v109, 0xffff0000, v53
	v_lshlrev_b32_e32 v110, 16, v61
	v_and_b32_e32 v111, 0xffff0000, v61
	v_lshlrev_b32_e32 v102, 16, v49
	v_and_b32_e32 v103, 0xffff0000, v49
	v_pk_mul_f32 v[114:115], v[18:19], v[108:109]
	v_pk_fma_f32 v[112:113], v[26:27], v[110:111], v[196:197]
	v_pk_mul_f32 v[94:95], v[62:63], v[114:115] op_sel_hi:[0,1]
	v_pk_mul_f32 v[78:79], v[112:113], v[108:109]
	v_pk_mul_f32 v[86:87], v[94:95], v[110:111]
	v_lshlrev_b32_e32 v104, 16, v63
	v_and_b32_e32 v105, 0xffff0000, v63
	s_waitcnt lgkmcnt(0)
	v_add_f32_e32 v125, v124, v125
	v_add_f32_e32 v126, v125, v126
	v_add_f32_e32 v127, v126, v127
	v_add_f32_e32 v128, v127, v128
	v_add_f32_e32 v129, v128, v129
	v_add_f32_e32 v130, v129, v130
	v_add_f32_e32 v131, v130, v131
	s_and_b32 s72, s6, 3
	s_lshl_b32 s72, s72, 10
	v_add_u32_e32 v182, s72, v180
	v_add_u32_e32 v183, s72, v175
	v_add_u32_e32 v146, 1, v146
	s_add_u32 s73, s6, 1
	s_mov_b32 s69, 0x100000

.Lsc_gf_go2:
	ds_read_b32 v185, v183
	s_waitcnt lgkmcnt(0)
	v_and_b32_e32 v185, v174, v185
	v_fma_f32 v189, v131, s14, v185
	ds_write_b32 v182, v189
	s_waitcnt lgkmcnt(0)
	ds_write_b32 v162, v146
	v_fma_f32 v124, v124, s14, v185
	v_fma_f32 v125, v125, s14, v185
	v_fma_f32 v126, v126, s14, v185
	v_fma_f32 v127, v127, s14, v185
	v_fma_f32 v128, v128, s14, v185
	v_fma_f32 v129, v129, s14, v185
	v_fma_f32 v130, v130, s14, v185
	v_fma_f32 v131, v131, s14, v185
	v_exp_f32_e64 v188, -v185
	v_exp_f32_e64 v124, -v124
	v_exp_f32_e64 v125, -v125
	v_exp_f32_e64 v126, -v126
	v_exp_f32_e64 v127, -v127
	v_exp_f32_e64 v128, -v128
	v_exp_f32_e64 v129, -v129
	v_exp_f32_e64 v130, -v130
	v_exp_f32_e64 v131, -v131
	s_nop 0
	ds_write_b32 v155, v188
	ds_write_b32 v155, v124 offset:256
	ds_write_b32 v155, v125 offset:512
	ds_write_b32 v155, v126 offset:768
	ds_write_b32 v155, v127 offset:1024
	ds_write_b32 v155, v128 offset:1280
	ds_write_b32 v155, v129 offset:1536
	ds_write_b32 v155, v130 offset:1792
	ds_write_b32 v155, v131 offset:2048
	v_mov_b32_e32 v161, v131
	s_waitcnt lgkmcnt(0)
	ds_read_b128 v[64:67], v153 offset:2048
	ds_read_b128 v[68:71], v153 offset:2176
	ds_read_b128 v[116:119], v153 offset:2304
	ds_read_b128 v[120:123], v153 offset:2432
	s_waitcnt lgkmcnt(0)
	v_rcp_f32_e32 v124, v116
	v_rcp_f32_e32 v125, v117
	v_rcp_f32_e32 v126, v118
	v_rcp_f32_e32 v127, v119
	v_rcp_f32_e32 v128, v120
	v_rcp_f32_e32 v129, v121
	v_rcp_f32_e32 v130, v122
	v_rcp_f32_e32 v131, v123
	s_nop 1
	v_pk_mul_f32 v[72:73], v[72:73], v[124:125]
	v_pk_mul_f32 v[80:81], v[80:81], v[124:125]
	v_pk_mul_f32 v[88:89], v[88:89], v[64:65]
	v_pk_mul_f32 v[96:97], v[96:97], v[116:117]
	v_pk_mul_f32 v[74:75], v[74:75], v[126:127]
	v_pk_mul_f32 v[82:83], v[82:83], v[126:127]
	v_pk_mul_f32 v[90:91], v[90:91], v[66:67]
	v_pk_mul_f32 v[98:99], v[98:99], v[118:119]
	v_pk_mul_f32 v[76:77], v[76:77], v[128:129]
	v_pk_mul_f32 v[84:85], v[84:85], v[128:129]
	v_pk_mul_f32 v[92:93], v[92:93], v[68:69]
	v_pk_mul_f32 v[100:101], v[100:101], v[120:121]
	v_pk_mul_f32 v[78:79], v[78:79], v[130:131]
	v_pk_mul_f32 v[86:87], v[86:87], v[130:131]
	v_pk_mul_f32 v[94:95], v[94:95], v[70:71]
	v_pk_mul_f32 v[102:103], v[102:103], v[122:123]
	global_load_dwordx2 v[46:47], v5, s[36:37]
	global_load_dwordx2 v[48:49], v5, s[36:37] offset:64
	global_load_dwordx2 v[50:51], v5, s[38:39]
	global_load_dwordx2 v[52:53], v5, s[38:39] offset:64
	global_load_dwordx2 v[54:55], v5, s[40:41]
	global_load_dwordx2 v[56:57], v5, s[40:41] offset:64
	global_load_dwordx2 v[58:59], v5, s[42:43]
	global_load_dwordx2 v[60:61], v5, s[42:43] offset:64
	global_load_dword v62, v6, s[46:47]
	global_load_dword v63, v9, s[44:45]
	v_add_u32_e32 v5, s54, v5
	v_add_u32_e32 v6, s55, v6
	v_add_u32_e32 v9, s54, v9
	ds_write_b32 v159, v161 offset:34816
	ds_write_b128 v8, v[72:75] offset:34816
	s_sleep 1
	ds_write_b128 v8, v[76:79] offset:34944
	ds_write_b128 v8, v[80:83] offset:35072
	s_sleep 1
	ds_write_b128 v8, v[84:87] offset:35200
	ds_write2_b32 v140, v96, v97 offset0:1 offset1:3
	s_sleep 1
	ds_write2_b32 v141, v88, v89 offset0:0 offset1:2
	ds_write2_b32 v140, v98, v99 offset0:65 offset1:67
	s_sleep 1
	ds_write2_b32 v141, v90, v91 offset0:64 offset1:66
	ds_write2_b32 v140, v100, v101 offset0:33 offset1:35
	s_sleep 1
	ds_write2_b32 v141, v92, v93 offset0:32 offset1:34
	ds_write2_b32 v140, v102, v103 offset0:97 offset1:99
	s_sleep 1
	ds_write2_b32 v141, v94, v95 offset0:96 offset1:98
	ds_write2_b32 v143, v104, v105 offset1:36
	s_sleep 1
	s_cmp_lg_u32 s7, 4
	s_cbranch_scc1 .Lsc_nokb2
	s_and_saveexec_b64 s[68:69], s[12:13]
	ds_write_b128 v158, v[88:91] offset:34816
	ds_write_b128 v158, v[92:95] offset:34944
	s_mov_b64 exec, s[68:69]
.Lsc_nokb2:
	s_add_i32 s6, s6, 1
	s_waitcnt lgkmcnt(0)
	ds_write_b32 v145, v146
.Lsc_G_loop:
	s_waitcnt vmcnt(10)
	v_lshlrev_b32_e32 v64, 16, v36
	v_and_b32_e32 v65, 0xffff0000, v36
	v_lshlrev_b32_e32 v66, 16, v37
	v_and_b32_e32 v67, 0xffff0000, v37
	v_lshlrev_b32_e32 v68, 16, v38
	v_and_b32_e32 v69, 0xffff0000, v38
	v_lshlrev_b32_e32 v70, 16, v39
	v_and_b32_e32 v71, 0xffff0000, v39
	ds_write_b128 v153, v[64:67]
	ds_write_b128 v153, v[68:71] offset:128
	s_waitcnt lgkmcnt(0)
	ds_read_b32 v124, v154 offset:0
	ds_read_b32 v125, v154 offset:256
	ds_read_b32 v126, v154 offset:512
	ds_read_b32 v127, v154 offset:768
	ds_read_b32 v128, v154 offset:1024
	ds_read_b32 v129, v154 offset:1280
	ds_read_b32 v130, v154 offset:1536
	ds_read_b32 v131, v154 offset:1792
	v_lshlrev_b32_e32 v108, 16, v32
	v_and_b32_e32 v109, 0xffff0000, v32
	v_lshlrev_b32_e32 v110, 16, v40
	v_and_b32_e32 v111, 0xffff0000, v40
	v_lshlrev_b32_e32 v96, 16, v28
	v_and_b32_e32 v97, 0xffff0000, v28
	v_pk_mul_f32 v[114:115], v[12:13], v[108:109]
	v_pk_fma_f32 v[112:113], v[20:21], v[110:111], v[190:191]
	v_pk_mul_f32 v[88:89], v[44:45], v[114:115] op_sel_hi:[0,1]
	v_pk_mul_f32 v[72:73], v[112:113], v[108:109]
	v_pk_mul_f32 v[80:81], v[88:89], v[110:111]
	v_lshlrev_b32_e32 v108, 16, v33
	v_and_b32_e32 v109, 0xffff0000, v33
	v_lshlrev_b32_e32 v110, 16, v41
	v_and_b32_e32 v111, 0xffff0000, v41
	v_lshlrev_b32_e32 v98, 16, v29
	v_and_b32_e32 v99, 0xffff0000, v29
	v_pk_mul_f32 v[114:115], v[14:15], v[108:109]
	v_pk_fma_f32 v[112:113], v[22:23], v[110:111], v[192:193]
	v_pk_mul_f32 v[90:91], v[44:45], v[114:115] op_sel_hi:[0,1]
	v_pk_mul_f32 v[74:75], v[112:113], v[108:109]
	v_pk_mul_f32 v[82:83], v[90:91], v[110:111]
	v_lshlrev_b32_e32 v108, 16, v34
	v_and_b32_e32 v109, 0xffff0000, v34
	v_lshlrev_b32_e32 v110, 16, v42
	v_and_b32_e32 v111, 0xffff0000, v42
	v_lshlrev_b32_e32 v100, 16, v30
	v_and_b32_e32 v101, 0xffff0000, v30
	v_pk_mul_f32 v[114:115], v[16:17], v[108:109]
	v_pk_fma_f32 v[112:113], v[24:25], v[110:111], v[194:195]
	v_pk_mul_f32 v[92:93], v[44:45], v[114:115] op_sel_hi:[0,1]
	v_pk_mul_f32 v[76:77], v[112:113], v[108:109]
	v_pk_mul_f32 v[84:85], v[92:93], v[110:111]
	v_lshlrev_b32_e32 v108, 16, v35
	v_and_b32_e32 v109, 0xffff0000, v35
	v_lshlrev_b32_e32 v110, 16, v43
	v_and_b32_e32 v111, 0xffff0000, v43
	v_lshlrev_b32_e32 v102, 16, v31
	v_and_b32_e32 v103, 0xffff0000, v31
	v_pk_mul_f32 v[114:115], v[18:19], v[108:109]
	v_pk_fma_f32 v[112:113], v[26:27], v[110:111], v[196:197]
	v_pk_mul_f32 v[94:95], v[44:45], v[114:115] op_sel_hi:[0,1]
	v_pk_mul_f32 v[78:79], v[112:113], v[108:109]
	v_pk_mul_f32 v[86:87], v[94:95], v[110:111]
	v_lshlrev_b32_e32 v104, 16, v45
	v_and_b32_e32 v105, 0xffff0000, v45
	s_waitcnt lgkmcnt(0)
	v_add_f32_e32 v125, v124, v125
	v_add_f32_e32 v126, v125, v126
	v_add_f32_e32 v127, v126, v127
	v_add_f32_e32 v128, v127, v128
	v_add_f32_e32 v129, v128, v129
	v_add_f32_e32 v130, v129, v130
	v_add_f32_e32 v131, v130, v131
	s_and_b32 s72, s6, 3
	s_lshl_b32 s72, s72, 10
	v_add_u32_e32 v182, s72, v180
	v_add_u32_e32 v183, s72, v175
	v_add_u32_e32 v146, 1, v146
	s_add_u32 s73, s6, 1
	s_mov_b32 s69, 0x100000

.Lsc_gf_go3:
	ds_read_b32 v185, v183
	s_waitcnt lgkmcnt(0)
	v_and_b32_e32 v185, v174, v185
	v_fma_f32 v189, v131, s14, v185
	ds_write_b32 v182, v189
	s_waitcnt lgkmcnt(0)
	ds_write_b32 v162, v146
	v_fma_f32 v124, v124, s14, v185
	v_fma_f32 v125, v125, s14, v185
	v_fma_f32 v126, v126, s14, v185
	v_fma_f32 v127, v127, s14, v185
	v_fma_f32 v128, v128, s14, v185
	v_fma_f32 v129, v129, s14, v185
	v_fma_f32 v130, v130, s14, v185
	v_fma_f32 v131, v131, s14, v185
	v_exp_f32_e64 v188, -v185
	v_exp_f32_e64 v124, -v124
	v_exp_f32_e64 v125, -v125
	v_exp_f32_e64 v126, -v126
	v_exp_f32_e64 v127, -v127
	v_exp_f32_e64 v128, -v128
	v_exp_f32_e64 v129, -v129
	v_exp_f32_e64 v130, -v130
	v_exp_f32_e64 v131, -v131
	s_nop 0
	ds_write_b32 v155, v188
	ds_write_b32 v155, v124 offset:256
	ds_write_b32 v155, v125 offset:512
	ds_write_b32 v155, v126 offset:768
	ds_write_b32 v155, v127 offset:1024
	ds_write_b32 v155, v128 offset:1280
	ds_write_b32 v155, v129 offset:1536
	ds_write_b32 v155, v130 offset:1792
	ds_write_b32 v155, v131 offset:2048
	v_mov_b32_e32 v161, v131
	s_waitcnt lgkmcnt(0)
	ds_read_b128 v[64:67], v153 offset:2048
	ds_read_b128 v[68:71], v153 offset:2176
	ds_read_b128 v[116:119], v153 offset:2304
	ds_read_b128 v[120:123], v153 offset:2432
	s_waitcnt lgkmcnt(0)
	v_rcp_f32_e32 v124, v116
	v_rcp_f32_e32 v125, v117
	v_rcp_f32_e32 v126, v118
	v_rcp_f32_e32 v127, v119
	v_rcp_f32_e32 v128, v120
	v_rcp_f32_e32 v129, v121
	v_rcp_f32_e32 v130, v122
	v_rcp_f32_e32 v131, v123
	s_nop 1
	v_pk_mul_f32 v[72:73], v[72:73], v[124:125]
	v_pk_mul_f32 v[80:81], v[80:81], v[124:125]
	v_pk_mul_f32 v[88:89], v[88:89], v[64:65]
	v_pk_mul_f32 v[96:97], v[96:97], v[116:117]
	v_pk_mul_f32 v[74:75], v[74:75], v[126:127]
	v_pk_mul_f32 v[82:83], v[82:83], v[126:127]
	v_pk_mul_f32 v[90:91], v[90:91], v[66:67]
	v_pk_mul_f32 v[98:99], v[98:99], v[118:119]
	v_pk_mul_f32 v[76:77], v[76:77], v[128:129]
	v_pk_mul_f32 v[84:85], v[84:85], v[128:129]
	v_pk_mul_f32 v[92:93], v[92:93], v[68:69]
	v_pk_mul_f32 v[100:101], v[100:101], v[120:121]
	v_pk_mul_f32 v[78:79], v[78:79], v[130:131]
	v_pk_mul_f32 v[86:87], v[86:87], v[130:131]
	v_pk_mul_f32 v[94:95], v[94:95], v[70:71]
	v_pk_mul_f32 v[102:103], v[102:103], v[122:123]
	global_load_dwordx2 v[28:29], v5, s[36:37]
	global_load_dwordx2 v[30:31], v5, s[36:37] offset:64
	global_load_dwordx2 v[32:33], v5, s[38:39]
	global_load_dwordx2 v[34:35], v5, s[38:39] offset:64
	global_load_dwordx2 v[36:37], v5, s[40:41]
	global_load_dwordx2 v[38:39], v5, s[40:41] offset:64
	global_load_dwordx2 v[40:41], v5, s[42:43]
	global_load_dwordx2 v[42:43], v5, s[42:43] offset:64
	global_load_dword v44, v6, s[46:47]
	global_load_dword v45, v9, s[44:45]
	v_add_u32_e32 v5, s54, v5
	v_add_u32_e32 v6, s55, v6
	v_add_u32_e32 v9, s54, v9
	s_sub_u32 s65, s6, 1
	ds_read_b128 v[148:151], v144
	s_waitcnt lgkmcnt(0)
	v_min_u32_e32 v148, v148, v149
	v_min3_u32 v148, v148, v150, v151
	s_nop 1
	v_readfirstlane_b32 s68, v148
	s_cmp_ge_u32 s68, s65
	s_cbranch_scc1 .Lsc_G_gom0
	s_mov_b32 s69, 0x100000

.Lsc_nokb3:
	ds_read_b128 v[106:109], v2 offset:0
	ds_read_b128 v[122:125], v2 offset:16384
	s_sleep 1
	ds_read_b128 v[110:113], v3 offset:0
	ds_read_b128 v[126:129], v3 offset:16384
	s_sleep 1
	ds_read_b128 v[114:117], v4 offset:0
	ds_read_b128 v[130:133], v4 offset:16384
	s_sleep 1
	ds_read_b128 v[118:121], v10 offset:0
	ds_read_b128 v[134:137], v10 offset:16384
	s_sleep 1
	s_waitcnt lgkmcnt(0)
	v_pk_add_f32 v[106:107], v[106:107], v[108:109]
	v_pk_add_f32 v[110:111], v[110:111], v[112:113]
	v_pk_add_f32 v[114:115], v[114:115], v[116:117]
	v_pk_add_f32 v[118:119], v[118:119], v[120:121]
	v_pk_add_f32 v[106:107], v[106:107], v[110:111]
	v_pk_add_f32 v[114:115], v[114:115], v[118:119]
	v_pk_add_f32 v[106:107], v[106:107], v[114:115]
	v_add_f32_e32 v64, v106, v107
	v_pk_add_f32 v[122:123], v[122:123], v[124:125]
	v_pk_add_f32 v[126:127], v[126:127], v[128:129]
	v_pk_add_f32 v[130:131], v[130:131], v[132:133]
	v_pk_add_f32 v[134:135], v[134:135], v[136:137]
	v_pk_add_f32 v[122:123], v[122:123], v[126:127]
	v_pk_add_f32 v[130:131], v[130:131], v[134:135]
	v_pk_add_f32 v[122:123], v[122:123], v[130:131]
	v_add_f32_e32 v65, v122, v123
	global_store_dword v7, v64, s[48:49]
	global_store_dword v165, v65, s[48:49]
	s_add_u32 s48, s48, s64
	s_addc_u32 s49, s49, s50
	s_add_i32 s6, s6, 1
	s_waitcnt lgkmcnt(0)
	ds_write_b32 v145, v146
	s_waitcnt vmcnt(10)
	v_lshlrev_b32_e32 v64, 16, v54
	v_and_b32_e32 v65, 0xffff0000, v54
	v_lshlrev_b32_e32 v66, 16, v55
	v_and_b32_e32 v67, 0xffff0000, v55
	v_lshlrev_b32_e32 v68, 16, v56
	v_and_b32_e32 v69, 0xffff0000, v56
	v_lshlrev_b32_e32 v70, 16, v57
	v_and_b32_e32 v71, 0xffff0000, v57
	ds_write_b128 v153, v[64:67]
	ds_write_b128 v153, v[68:71] offset:128
	s_waitcnt lgkmcnt(0)
	ds_read_b32 v124, v154 offset:0
	ds_read_b32 v125, v154 offset:256
	ds_read_b32 v126, v154 offset:512
	ds_read_b32 v127, v154 offset:768
	ds_read_b32 v128, v154 offset:1024
	ds_read_b32 v129, v154 offset:1280
	ds_read_b32 v130, v154 offset:1536
	ds_read_b32 v131, v154 offset:1792
	v_lshlrev_b32_e32 v108, 16, v50
	v_and_b32_e32 v109, 0xffff0000, v50
	v_lshlrev_b32_e32 v110, 16, v58
	v_and_b32_e32 v111, 0xffff0000, v58
	v_lshlrev_b32_e32 v96, 16, v46
	v_and_b32_e32 v97, 0xffff0000, v46
	v_pk_mul_f32 v[114:115], v[12:13], v[108:109]
	v_pk_fma_f32 v[112:113], v[20:21], v[110:111], v[190:191]
	v_pk_mul_f32 v[88:89], v[62:63], v[114:115] op_sel_hi:[0,1]
	v_pk_mul_f32 v[72:73], v[112:113], v[108:109]
	v_pk_mul_f32 v[80:81], v[88:89], v[110:111]
	v_lshlrev_b32_e32 v108, 16, v51
	v_and_b32_e32 v109, 0xffff0000, v51
	v_lshlrev_b32_e32 v110, 16, v59
	v_and_b32_e32 v111, 0xffff0000, v59
	v_lshlrev_b32_e32 v98, 16, v47
	v_and_b32_e32 v99, 0xffff0000, v47
	v_pk_mul_f32 v[114:115], v[14:15], v[108:109]
	v_pk_fma_f32 v[112:113], v[22:23], v[110:111], v[192:193]
	v_pk_mul_f32 v[90:91], v[62:63], v[114:115] op_sel_hi:[0,1]
	v_pk_mul_f32 v[74:75], v[112:113], v[108:109]
	v_pk_mul_f32 v[82:83], v[90:91], v[110:111]
	v_lshlrev_b32_e32 v108, 16, v52
	v_and_b32_e32 v109, 0xffff0000, v52
	v_lshlrev_b32_e32 v110, 16, v60
	v_and_b32_e32 v111, 0xffff0000, v60
	v_lshlrev_b32_e32 v100, 16, v48
	v_and_b32_e32 v101, 0xffff0000, v48
	v_pk_mul_f32 v[114:115], v[16:17], v[108:109]
	v_pk_fma_f32 v[112:113], v[24:25], v[110:111], v[194:195]
	v_pk_mul_f32 v[92:93], v[62:63], v[114:115] op_sel_hi:[0,1]
	v_pk_mul_f32 v[76:77], v[112:113], v[108:109]
	v_pk_mul_f32 v[84:85], v[92:93], v[110:111]
	v_lshlrev_b32_e32 v108, 16, v53
	v_and_b32_e32 v109, 0xffff0000, v53
	v_lshlrev_b32_e32 v110, 16, v61
	v_and_b32_e32 v111, 0xffff0000, v61
	v_lshlrev_b32_e32 v102, 16, v49
	v_and_b32_e32 v103, 0xffff0000, v49
	v_pk_mul_f32 v[114:115], v[18:19], v[108:109]
	v_pk_fma_f32 v[112:113], v[26:27], v[110:111], v[196:197]
	v_pk_mul_f32 v[94:95], v[62:63], v[114:115] op_sel_hi:[0,1]
	v_pk_mul_f32 v[78:79], v[112:113], v[108:109]
	v_pk_mul_f32 v[86:87], v[94:95], v[110:111]
	v_lshlrev_b32_e32 v104, 16, v63
	v_and_b32_e32 v105, 0xffff0000, v63
	s_waitcnt lgkmcnt(0)
	v_add_f32_e32 v125, v124, v125
	v_add_f32_e32 v126, v125, v126
	v_add_f32_e32 v127, v126, v127
	v_add_f32_e32 v128, v127, v128
	v_add_f32_e32 v129, v128, v129
	v_add_f32_e32 v130, v129, v130
	v_add_f32_e32 v131, v130, v131
	s_and_b32 s72, s6, 3
	s_lshl_b32 s72, s72, 10
	v_add_u32_e32 v182, s72, v180
	v_add_u32_e32 v183, s72, v175
	v_add_u32_e32 v146, 1, v146
	s_add_u32 s73, s6, 1
	s_mov_b32 s69, 0x100000

.Lsc_gf_go4:
	ds_read_b32 v185, v183
	s_waitcnt lgkmcnt(0)
	v_and_b32_e32 v185, v174, v185
	v_fma_f32 v189, v131, s14, v185
	ds_write_b32 v182, v189
	s_waitcnt lgkmcnt(0)
	ds_write_b32 v162, v146
	v_fma_f32 v124, v124, s14, v185
	v_fma_f32 v125, v125, s14, v185
	v_fma_f32 v126, v126, s14, v185
	v_fma_f32 v127, v127, s14, v185
	v_fma_f32 v128, v128, s14, v185
	v_fma_f32 v129, v129, s14, v185
	v_fma_f32 v130, v130, s14, v185
	v_fma_f32 v131, v131, s14, v185
	v_exp_f32_e64 v188, -v185
	v_exp_f32_e64 v124, -v124
	v_exp_f32_e64 v125, -v125
	v_exp_f32_e64 v126, -v126
	v_exp_f32_e64 v127, -v127
	v_exp_f32_e64 v128, -v128
	v_exp_f32_e64 v129, -v129
	v_exp_f32_e64 v130, -v130
	v_exp_f32_e64 v131, -v131
	s_nop 0
	ds_write_b32 v155, v188
	ds_write_b32 v155, v124 offset:256
	ds_write_b32 v155, v125 offset:512
	ds_write_b32 v155, v126 offset:768
	ds_write_b32 v155, v127 offset:1024
	ds_write_b32 v155, v128 offset:1280
	ds_write_b32 v155, v129 offset:1536
	ds_write_b32 v155, v130 offset:1792
	ds_write_b32 v155, v131 offset:2048
	v_mov_b32_e32 v161, v131
	s_waitcnt lgkmcnt(0)
	ds_read_b128 v[64:67], v153 offset:2048
	ds_read_b128 v[68:71], v153 offset:2176
	ds_read_b128 v[116:119], v153 offset:2304
	ds_read_b128 v[120:123], v153 offset:2432
	s_waitcnt lgkmcnt(0)
	v_rcp_f32_e32 v124, v116
	v_rcp_f32_e32 v125, v117
	v_rcp_f32_e32 v126, v118
	v_rcp_f32_e32 v127, v119
	v_rcp_f32_e32 v128, v120
	v_rcp_f32_e32 v129, v121
	v_rcp_f32_e32 v130, v122
	v_rcp_f32_e32 v131, v123
	s_nop 1
	v_pk_mul_f32 v[72:73], v[72:73], v[124:125]
	v_pk_mul_f32 v[80:81], v[80:81], v[124:125]
	v_pk_mul_f32 v[88:89], v[88:89], v[64:65]
	v_pk_mul_f32 v[96:97], v[96:97], v[116:117]
	v_pk_mul_f32 v[74:75], v[74:75], v[126:127]
	v_pk_mul_f32 v[82:83], v[82:83], v[126:127]
	v_pk_mul_f32 v[90:91], v[90:91], v[66:67]
	v_pk_mul_f32 v[98:99], v[98:99], v[118:119]
	v_pk_mul_f32 v[76:77], v[76:77], v[128:129]
	v_pk_mul_f32 v[84:85], v[84:85], v[128:129]
	v_pk_mul_f32 v[92:93], v[92:93], v[68:69]
	v_pk_mul_f32 v[100:101], v[100:101], v[120:121]
	v_pk_mul_f32 v[78:79], v[78:79], v[130:131]
	v_pk_mul_f32 v[86:87], v[86:87], v[130:131]
	v_pk_mul_f32 v[94:95], v[94:95], v[70:71]
	v_pk_mul_f32 v[102:103], v[102:103], v[122:123]
	global_load_dwordx2 v[46:47], v5, s[36:37]
	global_load_dwordx2 v[48:49], v5, s[36:37] offset:64
	global_load_dwordx2 v[50:51], v5, s[38:39]
	global_load_dwordx2 v[52:53], v5, s[38:39] offset:64
	global_load_dwordx2 v[54:55], v5, s[40:41]
	global_load_dwordx2 v[56:57], v5, s[40:41] offset:64
	global_load_dwordx2 v[58:59], v5, s[42:43]
	global_load_dwordx2 v[60:61], v5, s[42:43] offset:64
	global_load_dword v62, v6, s[46:47]
	global_load_dword v63, v9, s[44:45]
	v_add_u32_e32 v5, s54, v5
	v_add_u32_e32 v6, s55, v6
	v_add_u32_e32 v9, s54, v9
	s_sub_u32 s65, s6, 1
	ds_read_b128 v[148:151], v144
	s_waitcnt lgkmcnt(0)
	v_min_u32_e32 v148, v148, v149
	v_min3_u32 v148, v148, v150, v151
	s_nop 1
	v_readfirstlane_b32 s68, v148
	s_cmp_ge_u32 s68, s65
	s_cbranch_scc1 .Lsc_G_gom1
	s_mov_b32 s69, 0x100000

.Lsc_nokb4:
	ds_read_b128 v[106:109], v2 offset:32768
	ds_read_b128 v[122:125], v2 offset:49152
	s_sleep 1
	ds_read_b128 v[110:113], v3 offset:32768
	ds_read_b128 v[126:129], v3 offset:49152
	s_sleep 1
	ds_read_b128 v[114:117], v4 offset:32768
	ds_read_b128 v[130:133], v4 offset:49152
	s_sleep 1
	ds_read_b128 v[118:121], v10 offset:32768
	ds_read_b128 v[134:137], v10 offset:49152
	s_sleep 1
	s_waitcnt lgkmcnt(0)
	v_pk_add_f32 v[106:107], v[106:107], v[108:109]
	v_pk_add_f32 v[110:111], v[110:111], v[112:113]
	v_pk_add_f32 v[114:115], v[114:115], v[116:117]
	v_pk_add_f32 v[118:119], v[118:119], v[120:121]
	v_pk_add_f32 v[106:107], v[106:107], v[110:111]
	v_pk_add_f32 v[114:115], v[114:115], v[118:119]
	v_pk_add_f32 v[106:107], v[106:107], v[114:115]
	v_add_f32_e32 v64, v106, v107
	v_pk_add_f32 v[122:123], v[122:123], v[124:125]
	v_pk_add_f32 v[126:127], v[126:127], v[128:129]
	v_pk_add_f32 v[130:131], v[130:131], v[132:133]
	v_pk_add_f32 v[134:135], v[134:135], v[136:137]
	v_pk_add_f32 v[122:123], v[122:123], v[126:127]
	v_pk_add_f32 v[130:131], v[130:131], v[134:135]
	v_pk_add_f32 v[122:123], v[122:123], v[130:131]
	v_add_f32_e32 v65, v122, v123
	global_store_dword v7, v64, s[48:49]
	global_store_dword v165, v65, s[48:49]
	s_add_u32 s48, s48, s64
	s_addc_u32 s49, s49, s50
	s_add_i32 s6, s6, 1
	s_waitcnt lgkmcnt(0)
	ds_write_b32 v145, v146
	s_cmp_lt_u32 s6, 0xfe
	s_cbranch_scc1 .Lsc_G_loop
	s_waitcnt vmcnt(10)
	v_lshlrev_b32_e32 v64, 16, v36
	v_and_b32_e32 v65, 0xffff0000, v36
	v_lshlrev_b32_e32 v66, 16, v37
	v_and_b32_e32 v67, 0xffff0000, v37
	v_lshlrev_b32_e32 v68, 16, v38
	v_and_b32_e32 v69, 0xffff0000, v38
	v_lshlrev_b32_e32 v70, 16, v39
	v_and_b32_e32 v71, 0xffff0000, v39
	ds_write_b128 v153, v[64:67]
	ds_write_b128 v153, v[68:71] offset:128
	s_waitcnt lgkmcnt(0)
	ds_read_b32 v124, v154 offset:0
	ds_read_b32 v125, v154 offset:256
	ds_read_b32 v126, v154 offset:512
	ds_read_b32 v127, v154 offset:768
	ds_read_b32 v128, v154 offset:1024
	ds_read_b32 v129, v154 offset:1280
	ds_read_b32 v130, v154 offset:1536
	ds_read_b32 v131, v154 offset:1792
	v_lshlrev_b32_e32 v108, 16, v32
	v_and_b32_e32 v109, 0xffff0000, v32
	v_lshlrev_b32_e32 v110, 16, v40
	v_and_b32_e32 v111, 0xffff0000, v40
	v_lshlrev_b32_e32 v96, 16, v28
	v_and_b32_e32 v97, 0xffff0000, v28
	v_pk_mul_f32 v[114:115], v[12:13], v[108:109]
	v_pk_fma_f32 v[112:113], v[20:21], v[110:111], v[190:191]
	v_pk_mul_f32 v[88:89], v[44:45], v[114:115] op_sel_hi:[0,1]
	v_pk_mul_f32 v[72:73], v[112:113], v[108:109]
	v_pk_mul_f32 v[80:81], v[88:89], v[110:111]
	v_lshlrev_b32_e32 v108, 16, v33
	v_and_b32_e32 v109, 0xffff0000, v33
	v_lshlrev_b32_e32 v110, 16, v41
	v_and_b32_e32 v111, 0xffff0000, v41
	v_lshlrev_b32_e32 v98, 16, v29
	v_and_b32_e32 v99, 0xffff0000, v29
	v_pk_mul_f32 v[114:115], v[14:15], v[108:109]
	v_pk_fma_f32 v[112:113], v[22:23], v[110:111], v[192:193]
	v_pk_mul_f32 v[90:91], v[44:45], v[114:115] op_sel_hi:[0,1]
	v_pk_mul_f32 v[74:75], v[112:113], v[108:109]
	v_pk_mul_f32 v[82:83], v[90:91], v[110:111]
	v_lshlrev_b32_e32 v108, 16, v34
	v_and_b32_e32 v109, 0xffff0000, v34
	v_lshlrev_b32_e32 v110, 16, v42
	v_and_b32_e32 v111, 0xffff0000, v42
	v_lshlrev_b32_e32 v100, 16, v30
	v_and_b32_e32 v101, 0xffff0000, v30
	v_pk_mul_f32 v[114:115], v[16:17], v[108:109]
	v_pk_fma_f32 v[112:113], v[24:25], v[110:111], v[194:195]
	v_pk_mul_f32 v[92:93], v[44:45], v[114:115] op_sel_hi:[0,1]
	v_pk_mul_f32 v[76:77], v[112:113], v[108:109]
	v_pk_mul_f32 v[84:85], v[92:93], v[110:111]
	v_lshlrev_b32_e32 v108, 16, v35
	v_and_b32_e32 v109, 0xffff0000, v35
	v_lshlrev_b32_e32 v110, 16, v43
	v_and_b32_e32 v111, 0xffff0000, v43
	v_lshlrev_b32_e32 v102, 16, v31
	v_and_b32_e32 v103, 0xffff0000, v31
	v_pk_mul_f32 v[114:115], v[18:19], v[108:109]
	v_pk_fma_f32 v[112:113], v[26:27], v[110:111], v[196:197]
	v_pk_mul_f32 v[94:95], v[44:45], v[114:115] op_sel_hi:[0,1]
	v_pk_mul_f32 v[78:79], v[112:113], v[108:109]
	v_pk_mul_f32 v[86:87], v[94:95], v[110:111]
	v_lshlrev_b32_e32 v104, 16, v45
	v_and_b32_e32 v105, 0xffff0000, v45
	s_waitcnt lgkmcnt(0)
	v_add_f32_e32 v125, v124, v125
	v_add_f32_e32 v126, v125, v126
	v_add_f32_e32 v127, v126, v127
	v_add_f32_e32 v128, v127, v128
	v_add_f32_e32 v129, v128, v129
	v_add_f32_e32 v130, v129, v130
	v_add_f32_e32 v131, v130, v131
	s_and_b32 s72, s6, 3
	s_lshl_b32 s72, s72, 10
	v_add_u32_e32 v182, s72, v180
	v_add_u32_e32 v183, s72, v175
	v_add_u32_e32 v146, 1, v146
	s_add_u32 s73, s6, 1
	s_mov_b32 s69, 0x100000

.Lsc_gf_go5:
	ds_read_b32 v185, v183
	s_waitcnt lgkmcnt(0)
	v_and_b32_e32 v185, v174, v185
	v_fma_f32 v189, v131, s14, v185
	ds_write_b32 v182, v189
	s_waitcnt lgkmcnt(0)
	ds_write_b32 v162, v146
	v_fma_f32 v124, v124, s14, v185
	v_fma_f32 v125, v125, s14, v185
	v_fma_f32 v126, v126, s14, v185
	v_fma_f32 v127, v127, s14, v185
	v_fma_f32 v128, v128, s14, v185
	v_fma_f32 v129, v129, s14, v185
	v_fma_f32 v130, v130, s14, v185
	v_fma_f32 v131, v131, s14, v185
	v_exp_f32_e64 v188, -v185
	v_exp_f32_e64 v124, -v124
	v_exp_f32_e64 v125, -v125
	v_exp_f32_e64 v126, -v126
	v_exp_f32_e64 v127, -v127
	v_exp_f32_e64 v128, -v128
	v_exp_f32_e64 v129, -v129
	v_exp_f32_e64 v130, -v130
	v_exp_f32_e64 v131, -v131
	s_nop 0
	ds_write_b32 v155, v188
	ds_write_b32 v155, v124 offset:256
	ds_write_b32 v155, v125 offset:512
	ds_write_b32 v155, v126 offset:768
	ds_write_b32 v155, v127 offset:1024
	ds_write_b32 v155, v128 offset:1280
	ds_write_b32 v155, v129 offset:1536
	ds_write_b32 v155, v130 offset:1792
	ds_write_b32 v155, v131 offset:2048
	v_mov_b32_e32 v161, v131
	s_waitcnt lgkmcnt(0)
	ds_read_b128 v[64:67], v153 offset:2048
	ds_read_b128 v[68:71], v153 offset:2176
	ds_read_b128 v[116:119], v153 offset:2304
	ds_read_b128 v[120:123], v153 offset:2432
	s_waitcnt lgkmcnt(0)
	v_rcp_f32_e32 v124, v116
	v_rcp_f32_e32 v125, v117
	v_rcp_f32_e32 v126, v118
	v_rcp_f32_e32 v127, v119
	v_rcp_f32_e32 v128, v120
	v_rcp_f32_e32 v129, v121
	v_rcp_f32_e32 v130, v122
	v_rcp_f32_e32 v131, v123
	s_nop 1
	v_pk_mul_f32 v[72:73], v[72:73], v[124:125]
	v_pk_mul_f32 v[80:81], v[80:81], v[124:125]
	v_pk_mul_f32 v[88:89], v[88:89], v[64:65]
	v_pk_mul_f32 v[96:97], v[96:97], v[116:117]
	v_pk_mul_f32 v[74:75], v[74:75], v[126:127]
	v_pk_mul_f32 v[82:83], v[82:83], v[126:127]
	v_pk_mul_f32 v[90:91], v[90:91], v[66:67]
	v_pk_mul_f32 v[98:99], v[98:99], v[118:119]
	v_pk_mul_f32 v[76:77], v[76:77], v[128:129]
	v_pk_mul_f32 v[84:85], v[84:85], v[128:129]
	v_pk_mul_f32 v[92:93], v[92:93], v[68:69]
	v_pk_mul_f32 v[100:101], v[100:101], v[120:121]
	v_pk_mul_f32 v[78:79], v[78:79], v[130:131]
	v_pk_mul_f32 v[86:87], v[86:87], v[130:131]
	v_pk_mul_f32 v[94:95], v[94:95], v[70:71]
	v_pk_mul_f32 v[102:103], v[102:103], v[122:123]
	s_sub_u32 s65, s6, 1
	ds_read_b128 v[148:151], v144
	s_waitcnt lgkmcnt(0)
	v_min_u32_e32 v148, v148, v149
	v_min3_u32 v148, v148, v150, v151
	s_nop 1
	v_readfirstlane_b32 s68, v148
	s_cmp_ge_u32 s68, s65
	s_cbranch_scc1 .Lsc_G_goz0
	s_mov_b32 s69, 0x100000

.Lsc_nokb5:
	ds_read_b128 v[106:109], v2 offset:0
	ds_read_b128 v[122:125], v2 offset:16384
	s_sleep 1
	ds_read_b128 v[110:113], v3 offset:0
	ds_read_b128 v[126:129], v3 offset:16384
	s_sleep 1
	ds_read_b128 v[114:117], v4 offset:0
	ds_read_b128 v[130:133], v4 offset:16384
	s_sleep 1
	ds_read_b128 v[118:121], v10 offset:0
	ds_read_b128 v[134:137], v10 offset:16384
	s_sleep 1
	s_waitcnt lgkmcnt(0)
	v_pk_add_f32 v[106:107], v[106:107], v[108:109]
	v_pk_add_f32 v[110:111], v[110:111], v[112:113]
	v_pk_add_f32 v[114:115], v[114:115], v[116:117]
	v_pk_add_f32 v[118:119], v[118:119], v[120:121]
	v_pk_add_f32 v[106:107], v[106:107], v[110:111]
	v_pk_add_f32 v[114:115], v[114:115], v[118:119]
	v_pk_add_f32 v[106:107], v[106:107], v[114:115]
	v_add_f32_e32 v64, v106, v107
	v_pk_add_f32 v[122:123], v[122:123], v[124:125]
	v_pk_add_f32 v[126:127], v[126:127], v[128:129]
	v_pk_add_f32 v[130:131], v[130:131], v[132:133]
	v_pk_add_f32 v[134:135], v[134:135], v[136:137]
	v_pk_add_f32 v[122:123], v[122:123], v[126:127]
	v_pk_add_f32 v[130:131], v[130:131], v[134:135]
	v_pk_add_f32 v[122:123], v[122:123], v[130:131]
	v_add_f32_e32 v65, v122, v123
	global_store_dword v7, v64, s[48:49]
	global_store_dword v165, v65, s[48:49]
	s_add_u32 s48, s48, s64
	s_addc_u32 s49, s49, s50
	s_add_i32 s6, s6, 1
	s_waitcnt lgkmcnt(0)
	ds_write_b32 v145, v146
	s_waitcnt vmcnt(0)
	v_lshlrev_b32_e32 v64, 16, v54
	v_and_b32_e32 v65, 0xffff0000, v54
	v_lshlrev_b32_e32 v66, 16, v55
	v_and_b32_e32 v67, 0xffff0000, v55
	v_lshlrev_b32_e32 v68, 16, v56
	v_and_b32_e32 v69, 0xffff0000, v56
	v_lshlrev_b32_e32 v70, 16, v57
	v_and_b32_e32 v71, 0xffff0000, v57
	ds_write_b128 v153, v[64:67]
	ds_write_b128 v153, v[68:71] offset:128
	s_waitcnt lgkmcnt(0)
	ds_read_b32 v124, v154 offset:0
	ds_read_b32 v125, v154 offset:256
	ds_read_b32 v126, v154 offset:512
	ds_read_b32 v127, v154 offset:768
	ds_read_b32 v128, v154 offset:1024
	ds_read_b32 v129, v154 offset:1280
	ds_read_b32 v130, v154 offset:1536
	ds_read_b32 v131, v154 offset:1792
	v_lshlrev_b32_e32 v108, 16, v50
	v_and_b32_e32 v109, 0xffff0000, v50
	v_lshlrev_b32_e32 v110, 16, v58
	v_and_b32_e32 v111, 0xffff0000, v58
	v_lshlrev_b32_e32 v96, 16, v46
	v_and_b32_e32 v97, 0xffff0000, v46
	v_pk_mul_f32 v[114:115], v[12:13], v[108:109]
	v_pk_fma_f32 v[112:113], v[20:21], v[110:111], v[190:191]
	v_pk_mul_f32 v[88:89], v[62:63], v[114:115] op_sel_hi:[0,1]
	v_pk_mul_f32 v[72:73], v[112:113], v[108:109]
	v_pk_mul_f32 v[80:81], v[88:89], v[110:111]
	v_lshlrev_b32_e32 v108, 16, v51
	v_and_b32_e32 v109, 0xffff0000, v51
	v_lshlrev_b32_e32 v110, 16, v59
	v_and_b32_e32 v111, 0xffff0000, v59
	v_lshlrev_b32_e32 v98, 16, v47
	v_and_b32_e32 v99, 0xffff0000, v47
	v_pk_mul_f32 v[114:115], v[14:15], v[108:109]
	v_pk_fma_f32 v[112:113], v[22:23], v[110:111], v[192:193]
	v_pk_mul_f32 v[90:91], v[62:63], v[114:115] op_sel_hi:[0,1]
	v_pk_mul_f32 v[74:75], v[112:113], v[108:109]
	v_pk_mul_f32 v[82:83], v[90:91], v[110:111]
	v_lshlrev_b32_e32 v108, 16, v52
	v_and_b32_e32 v109, 0xffff0000, v52
	v_lshlrev_b32_e32 v110, 16, v60
	v_and_b32_e32 v111, 0xffff0000, v60
	v_lshlrev_b32_e32 v100, 16, v48
	v_and_b32_e32 v101, 0xffff0000, v48
	v_pk_mul_f32 v[114:115], v[16:17], v[108:109]
	v_pk_fma_f32 v[112:113], v[24:25], v[110:111], v[194:195]
	v_pk_mul_f32 v[92:93], v[62:63], v[114:115] op_sel_hi:[0,1]
	v_pk_mul_f32 v[76:77], v[112:113], v[108:109]
	v_pk_mul_f32 v[84:85], v[92:93], v[110:111]
	v_lshlrev_b32_e32 v108, 16, v53
	v_and_b32_e32 v109, 0xffff0000, v53
	v_lshlrev_b32_e32 v110, 16, v61
	v_and_b32_e32 v111, 0xffff0000, v61
	v_lshlrev_b32_e32 v102, 16, v49
	v_and_b32_e32 v103, 0xffff0000, v49
	v_pk_mul_f32 v[114:115], v[18:19], v[108:109]
	v_pk_fma_f32 v[112:113], v[26:27], v[110:111], v[196:197]
	v_pk_mul_f32 v[94:95], v[62:63], v[114:115] op_sel_hi:[0,1]
	v_pk_mul_f32 v[78:79], v[112:113], v[108:109]
	v_pk_mul_f32 v[86:87], v[94:95], v[110:111]
	v_lshlrev_b32_e32 v104, 16, v63
	v_and_b32_e32 v105, 0xffff0000, v63
	s_waitcnt lgkmcnt(0)
	v_add_f32_e32 v125, v124, v125
	v_add_f32_e32 v126, v125, v126
	v_add_f32_e32 v127, v126, v127
	v_add_f32_e32 v128, v127, v128
	v_add_f32_e32 v129, v128, v129
	v_add_f32_e32 v130, v129, v130
	v_add_f32_e32 v131, v130, v131
	s_and_b32 s72, s6, 3
	s_lshl_b32 s72, s72, 10
	v_add_u32_e32 v182, s72, v180
	v_add_u32_e32 v183, s72, v175
	v_add_u32_e32 v146, 1, v146
	s_add_u32 s73, s6, 1
	s_mov_b32 s69, 0x100000

.Lsc_nokb6:
	ds_read_b128 v[106:109], v2 offset:32768
	ds_read_b128 v[122:125], v2 offset:49152
	s_sleep 1
	ds_read_b128 v[110:113], v3 offset:32768
	ds_read_b128 v[126:129], v3 offset:49152
	s_sleep 1
	ds_read_b128 v[114:117], v4 offset:32768
	ds_read_b128 v[130:133], v4 offset:49152
	s_sleep 1
	ds_read_b128 v[118:121], v10 offset:32768
	ds_read_b128 v[134:137], v10 offset:49152
	s_sleep 1
	s_waitcnt lgkmcnt(0)
	v_pk_add_f32 v[106:107], v[106:107], v[108:109]
	v_pk_add_f32 v[110:111], v[110:111], v[112:113]
	v_pk_add_f32 v[114:115], v[114:115], v[116:117]
	v_pk_add_f32 v[118:119], v[118:119], v[120:121]
	v_pk_add_f32 v[106:107], v[106:107], v[110:111]
	v_pk_add_f32 v[114:115], v[114:115], v[118:119]
	v_pk_add_f32 v[106:107], v[106:107], v[114:115]
	v_add_f32_e32 v64, v106, v107
	v_pk_add_f32 v[122:123], v[122:123], v[124:125]
	v_pk_add_f32 v[126:127], v[126:127], v[128:129]
	v_pk_add_f32 v[130:131], v[130:131], v[132:133]
	v_pk_add_f32 v[134:135], v[134:135], v[136:137]
	v_pk_add_f32 v[122:123], v[122:123], v[126:127]
	v_pk_add_f32 v[130:131], v[130:131], v[134:135]
	v_pk_add_f32 v[122:123], v[122:123], v[130:131]
	v_add_f32_e32 v65, v122, v123
	global_store_dword v7, v64, s[48:49]
	global_store_dword v165, v65, s[48:49]
	s_add_u32 s48, s48, s64
	s_addc_u32 s49, s49, s50
	s_add_i32 s6, s6, 1
	s_waitcnt lgkmcnt(0)
	ds_write_b32 v145, v146
	s_sub_u32 s65, s6, 1
	ds_read_b128 v[148:151], v144
	s_waitcnt lgkmcnt(0)
	v_min_u32_e32 v148, v148, v149
	v_min3_u32 v148, v148, v150, v151
	s_nop 1
	v_readfirstlane_b32 s68, v148
	s_cmp_ge_u32 s68, s65
	s_cbranch_scc1 .Lsc_G_goz2
	s_mov_b32 s69, 0x100000
